# attention: next-tile K/V LDS staging writes issued right after the QK MFMAs for active waves (no LDS write latency before the tile barrier), V-fragment lgkmcnt waits rebased
# baseline (speedup 1.0000x reference)
.Latt_t2:
	s_waitcnt lgkmcnt(0)
	s_barrier

; #define LAS __attribute__((address_space(3)))
; __device__ __forceinline__ void qk_tile(f32x16& s0, f32x16& s1, LAS unsigned char* kb, const bf16x8 (&qr)[6], const f32x16& negm, int r32, int hi) {
;     bf16x8 kf[12];
; #pragma unroll
;     for (int ks = 0; ks < 6; ++ks) { kf[2 * ks] = *(const LAS bf16x8*)(kb + r32 * KPT + ks * 32 + hi * 16); kf[2 * ks + 1] = *(const LAS bf16x8*)(kb + (32 + r32) * KPT + ks * 32 + hi * 16); }
;     __builtin_amdgcn_sched_barrier(0);
; #pragma unroll
;     for (int ks = 0; ks < 6; ++ks) {
;         s0 = __builtin_amdgcn_mfma_f32_32x32x16_bf16(kf[2 * ks], qr[ks], ks == 0 ? negm : s0, 0, 0, 0);
;         s1 = __builtin_amdgcn_mfma_f32_32x32x16_bf16(kf[2 * ks + 1], qr[ks], ks == 0 ? negm : s1, 0, 0, 0);
;     }
; }
.LBB0_418:
	s_add_i32 s85, s84, -3
	s_cmp_lt_u32 s85, s57
	s_cselect_b64 s[44:45], -1, 0
	s_and_b64 s[4:5], s[44:45], exec
	s_cselect_b32 s4, 0, s79
	s_lshl_b32 s4, s4, 6
	v_add_u32_e32 v221, s83, v213
	v_add_u32_e32 v222, s83, v173
	s_sub_i32 s5, 0x80, s4
	v_cmp_le_u32_e32 vcc, s83, v220
	s_and_saveexec_b64 s[46:47], vcc
	s_cbranch_execz .Latt_sk1
	ds_read_b128 v[10:13], v240 offset:13312
	ds_read_b128 v[136:139], v240 offset:13344
	ds_read_b128 v[140:143], v240 offset:19968
	ds_read_b128 v[144:147], v240 offset:20000
	ds_read_b128 v[148:151], v240 offset:13376
	ds_read_b128 v[152:155], v240 offset:13408
	ds_read_b128 v[156:159], v240 offset:20032
	ds_read_b128 v[160:163], v240 offset:20064
	ds_read_b128 v[224:227], v240 offset:13440
	ds_read_b128 v[228:231], v240 offset:13472
	ds_read_b128 v[232:235], v240 offset:20096
	ds_read_b128 v[246:249], v240 offset:20128
	s_waitcnt lgkmcnt(11)
	v_mfma_f32_32x32x16_bf16 v[80:95], v[10:13], v[96:99], v[48:63]
	s_add_i32 s4, s83, 63
	v_cmp_gt_i32_e32 vcc, s4, v175
	s_waitcnt lgkmcnt(9)
	v_mfma_f32_32x32x16_bf16 v[64:79], v[140:143], v[96:99], v[48:63]
	v_mfma_f32_32x32x16_bf16 v[80:95], v[136:139], v[100:103], v[80:95]
	s_waitcnt lgkmcnt(8)
	v_mfma_f32_32x32x16_bf16 v[64:79], v[144:147], v[100:103], v[64:79]
	s_waitcnt lgkmcnt(7)
	v_mfma_f32_32x32x16_bf16 v[80:95], v[148:151], v[104:107], v[80:95]
	s_waitcnt lgkmcnt(5)
	v_mfma_f32_32x32x16_bf16 v[64:79], v[156:159], v[104:107], v[64:79]
	v_mfma_f32_32x32x16_bf16 v[80:95], v[152:155], v[108:111], v[80:95]
	ds_read2_b64 v[152:155], v250 offset0:68 offset1:70
	s_waitcnt lgkmcnt(5)
	v_mfma_f32_32x32x16_bf16 v[64:79], v[160:163], v[108:111], v[64:79]
	ds_read2_b64 v[160:163], v250 offset0:64 offset1:66
	ds_read2_b64 v[156:159], v251 offset0:96 offset1:98
	ds_read2_b64 v[148:151], v251 offset0:100 offset1:102
	ds_read2_b64 v[144:147], v250 offset0:72 offset1:74
	ds_read2_b64 v[140:143], v251 offset0:104 offset1:106
	ds_read2_b64 v[136:139], v250 offset0:76 offset1:78
	ds_read2_b64 v[10:13], v251 offset0:108 offset1:110
	s_waitcnt lgkmcnt(11)
	v_mfma_f32_32x32x16_bf16 v[80:95], v[224:227], v[112:115], v[80:95]
	s_waitcnt lgkmcnt(9)
	v_mfma_f32_32x32x16_bf16 v[64:79], v[232:235], v[112:115], v[64:79]
	v_mfma_f32_32x32x16_bf16 v[80:95], v[228:231], v[116:119], v[80:95]
	s_waitcnt lgkmcnt(8)
	v_mfma_f32_32x32x16_bf16 v[64:79], v[246:249], v[116:119], v[64:79]
	s_waitcnt vmcnt(0)
	ds_write_b128 v210, v[120:123]
	s_and_saveexec_b64 s[6:7], s[2:3]
	ds_write_b128 v210, v[124:127] offset:128
	s_or_b64 exec, exec, s[6:7]
	v_perm_b32 v2, v186, v184, s94
	v_perm_b32 v3, v186, v184, s95
	ds_write2_b32 v214, v2, v3 offset1:34
	v_perm_b32 v2, v187, v185, s94
	v_perm_b32 v3, v187, v185, s95
	ds_write2_b32 v214, v2, v3 offset0:68 offset1:102
	s_waitcnt vmcnt(3)
	v_add_u32_e32 v2, s5, v221
	v_add_u32_e32 v14, s5, v222
	v_min_u32_e32 v2, 0x80ff, v2
	v_add_u32_e32 v192, 1, v14
	v_min_u32_e32 v14, 0x80ff, v14
	v_min_u32_e32 v192, 0x80ff, v192
	v_lshl_add_u32 v4, v2, 12, v238
	s_waitcnt vmcnt(2)
	v_lshl_add_u32 v6, v2, 6, v239
	v_lshl_add_u32 v14, v14, 12, v174
	v_lshl_add_u32 v192, v192, 12, v174
	global_load_dwordx4 v[2:5], v4, s[98:99]
	s_nop 0
	global_load_dwordx4 v[6:9], v6, s[100:101]
	global_load_dwordx2 v[14:15], v14, s[98:99] offset:128
	global_load_dwordx2 v[192:193], v192, s[98:99] offset:128
	s_and_saveexec_b64 s[58:59], vcc
	s_cbranch_execz .LBB0_423
; __device__ __forceinline__ void sm_pv(f32x16& s0, f32x16& s1, f32x16& o0, f32x16& o1, float& m_run, float& l_run, f32x16& negm, LAS unsigned char* vb, bool domask, int kbase, int qm, int r32, int hi) {
;     ...
;     if (domask) {
;         const int kb0 = kbase + 4 * hi;
; #pragma unroll
;         for (int r = 0; r < 16; ++r) { const int kv = kb0 + (r & 3) + 8 * (r >> 2); if (kv > qm) s0[r] = -INFINITY; if (kv + 32 > qm) s1[r] = -INFINITY; }
;     }
	v_add_u32_e32 v223, s83, v201
	v_add_u32_e32 v224, 32, v223
	v_cmp_ge_i32_e64 s[4:5], v177, v224
	v_add_u32_e32 v224, 33, v223
	v_cmp_ge_i32_e64 s[6:7], v177, v224
	v_add_u32_e32 v224, 2, v223
	v_cmp_le_u32_e32 vcc, v223, v219
	s_nop 2
	v_cndmask_b32_e64 v65, v244, v65, s[6:7]
	v_cmp_ge_i32_e64 s[6:7], v177, v224
	v_add_u32_e32 v224, 34, v223
	v_cmp_ge_i32_e64 s[8:9], v177, v224
	v_add_u32_e32 v224, 3, v223
	v_cndmask_b32_e64 v64, v244, v64, s[4:5]
	v_cndmask_b32_e64 v66, v244, v66, s[8:9]
	v_cmp_ge_i32_e64 s[8:9], v177, v224
	v_add_u32_e32 v224, 35, v223
	v_cmp_ge_i32_e64 s[10:11], v177, v224
	v_add_u32_e32 v224, 8, v223
	v_cmp_gt_i32_e64 s[4:5], v177, v223
	v_cndmask_b32_e64 v67, v244, v67, s[10:11]
	v_cmp_ge_i32_e64 s[10:11], v177, v224
	v_add_u32_e32 v224, 40, v223
	v_cmp_ge_i32_e64 s[12:13], v177, v224
	v_add_u32_e32 v224, 9, v223
	s_nop 0
	v_cndmask_b32_e64 v68, v244, v68, s[12:13]
	v_cmp_ge_i32_e64 s[12:13], v177, v224
	v_add_u32_e32 v224, 41, v223
	v_cmp_ge_i32_e64 s[14:15], v177, v224
	v_add_u32_e32 v224, 10, v223
	s_nop 0
	v_cndmask_b32_e64 v69, v244, v69, s[14:15]
	v_cmp_ge_i32_e64 s[14:15], v177, v224
	v_add_u32_e32 v224, 42, v223
	v_cmp_ge_i32_e64 s[16:17], v177, v224
	v_add_u32_e32 v224, 11, v223
	s_nop 0
	v_cndmask_b32_e64 v70, v244, v70, s[16:17]
	v_cmp_ge_i32_e64 s[16:17], v177, v224
	v_add_u32_e32 v224, 43, v223
	v_cmp_ge_i32_e64 s[18:19], v177, v224
	v_add_u32_e32 v224, 16, v223
	s_nop 0
	v_cndmask_b32_e64 v71, v244, v71, s[18:19]
	v_cmp_ge_i32_e64 s[18:19], v177, v224
	v_add_u32_e32 v224, 48, v223
	v_cmp_ge_i32_e64 s[20:21], v177, v224
	v_add_u32_e32 v224, 17, v223
	s_nop 0
	v_cndmask_b32_e64 v72, v244, v72, s[20:21]
	v_cmp_ge_i32_e64 s[20:21], v177, v224
	v_add_u32_e32 v224, 49, v223
	v_cmp_ge_i32_e64 s[22:23], v177, v224
	v_add_u32_e32 v224, 18, v223
	s_nop 0
	v_cndmask_b32_e64 v73, v244, v73, s[22:23]
	v_cmp_ge_i32_e64 s[22:23], v177, v224
	v_add_u32_e32 v224, 50, v223
	v_cmp_ge_i32_e64 s[24:25], v177, v224
	v_add_u32_e32 v224, 19, v223
	s_nop 0
	v_cndmask_b32_e64 v74, v244, v74, s[24:25]
	v_cmp_ge_i32_e64 s[24:25], v177, v224
	v_add_u32_e32 v224, 51, v223
	v_cmp_ge_i32_e64 s[26:27], v177, v224
	v_add_u32_e32 v224, 24, v223
	s_nop 0
	v_cndmask_b32_e64 v75, v244, v75, s[26:27]
	v_cmp_ge_i32_e64 s[26:27], v177, v224
	v_add_u32_e32 v224, 56, v223
	v_cmp_ge_i32_e64 s[28:29], v177, v224
	v_add_u32_e32 v224, 25, v223
	s_nop 0
	v_cndmask_b32_e64 v76, v244, v76, s[28:29]
	v_cmp_ge_i32_e64 s[28:29], v177, v224
	v_add_u32_e32 v224, 57, v223
	v_cmp_ge_i32_e64 s[30:31], v177, v224
	v_add_u32_e32 v224, 26, v223
	s_nop 0
	v_cndmask_b32_e64 v77, v244, v77, s[30:31]
	v_cmp_ge_i32_e64 s[30:31], v177, v224
	v_add_u32_e32 v224, 58, v223
	v_cmp_ge_i32_e64 s[34:35], v177, v224
	v_add_u32_e32 v224, 27, v223
	v_add_u32_e32 v223, 59, v223
	v_cndmask_b32_e64 v78, v244, v78, s[34:35]
	v_cmp_ge_i32_e64 s[34:35], v177, v224
	v_cmp_lt_i32_e64 s[36:37], v177, v223
	s_and_saveexec_b64 s[40:41], s[36:37]
	v_mov_b32_e32 v79, s52
	s_or_b64 exec, exec, s[40:41]
	v_cndmask_b32_e32 v80, v244, v80, vcc
	v_cndmask_b32_e64 v81, v244, v81, s[4:5]
	v_cndmask_b32_e64 v82, v244, v82, s[6:7]
	v_cndmask_b32_e64 v83, v244, v83, s[8:9]
	v_cndmask_b32_e64 v84, v244, v84, s[10:11]
	v_cndmask_b32_e64 v85, v244, v85, s[12:13]
	v_cndmask_b32_e64 v86, v244, v86, s[14:15]
	v_cndmask_b32_e64 v87, v244, v87, s[16:17]
	v_cndmask_b32_e64 v88, v244, v88, s[18:19]
	v_cndmask_b32_e64 v89, v244, v89, s[20:21]
	v_cndmask_b32_e64 v90, v244, v90, s[22:23]
	v_cndmask_b32_e64 v91, v244, v91, s[24:25]
	v_cndmask_b32_e64 v92, v244, v92, s[26:27]
	v_cndmask_b32_e64 v93, v244, v93, s[28:29]
	v_cndmask_b32_e64 v94, v244, v94, s[30:31]
	v_cndmask_b32_e64 v95, v244, v95, s[34:35]

; __device__ __forceinline__ unsigned cvtpk(float lo, float hi) { const f32x2 v = {lo, hi}; const bf16x2_t b = __builtin_convertvector(v, bf16x2_t); return __builtin_bit_cast(unsigned, b); }
; __device__ __forceinline__ void sm_pv(f32x16& s0, f32x16& s1, f32x16& o0, f32x16& o1, float& m_run, float& l_run, f32x16& negm, LAS unsigned char* vb, bool domask, int kbase, int qm, int r32, int hi) {
;     ...
;     f32x2 ps2 = (f32x2){0.f, 0.f};
; #pragma unroll
;     for (int r = 0; r < 16; r += 2) { s0[r] = __builtin_amdgcn_exp2f(s0[r]); s0[r + 1] = __builtin_amdgcn_exp2f(s0[r + 1]); s1[r] = __builtin_amdgcn_exp2f(s1[r]); s1[r + 1] = __builtin_amdgcn_exp2f(s1[r + 1]);
;         ps2 += (f32x2){s0[r], s0[r + 1]}; ps2 += (f32x2){s1[r], s1[r + 1]}; }
;     l_run += ps2[0] + ps2[1];
;     u32x4 pw[4];
; #pragma unroll
;     for (int i = 0; i < 4; ++i) { pw[0][i] = cvtpk(s0[2 * i], s0[2 * i + 1]); pw[1][i] = cvtpk(s0[8 + 2 * i], s0[8 + 2 * i + 1]); pw[2][i] = cvtpk(s1[2 * i], s1[2 * i + 1]); pw[3][i] = cvtpk(s1[8 + 2 * i], s1[8 + 2 * i + 1]); }
; #pragma unroll
;     for (int kk = 0; kk < 4; ++kk) {
;         const bf16x8 pf = __builtin_bit_cast(bf16x8, pw[kk]);
;         { const s16x4 lo = vlo[2 * kk], hh = vhh[2 * kk];
;           const bf16x8 vf = (bf16x8){lo[0], lo[1], lo[2], lo[3], hh[0], hh[1], hh[2], hh[3]};
;           o0 = __builtin_amdgcn_mfma_f32_32x32x16_bf16(vf, pf, o0, 0, 0, 0); }
;         { const s16x4 lo = vlo[2 * kk + 1], hh = vhh[2 * kk + 1];
;           const bf16x8 vf = (bf16x8){lo[0], lo[1], lo[2], lo[3], hh[0], hh[1], hh[2], hh[3]};
;           o1 = __builtin_amdgcn_mfma_f32_32x32x16_bf16(vf, pf, o1, 0, 0, 0); }
;     }
.LBB0_425:
	v_exp_f32_e32 v80, v80
	v_exp_f32_e32 v81, v81
	v_exp_f32_e32 v228, v82
	v_exp_f32_e32 v229, v83
	v_exp_f32_e32 v84, v84
	v_exp_f32_e32 v85, v85
	v_exp_f32_e32 v86, v86
	v_exp_f32_e32 v87, v87
	v_exp_f32_e32 v224, v64
	v_exp_f32_e32 v225, v65
	v_add_f32_e32 v64, 0, v80
	v_add_f32_e32 v65, 0, v81
	v_cvt_pk_bf16_f32 v80, v80, v81
	v_cvt_pk_bf16_f32 v81, v228, v229
	v_cvt_pk_bf16_f32 v82, v84, v85
	v_cvt_pk_bf16_f32 v83, v86, v87
	v_exp_f32_e32 v88, v88
	v_exp_f32_e32 v89, v89
	s_waitcnt lgkmcnt(10)
	v_mfma_f32_32x32x16_bf16 v[32:47], v[160:163], v[80:83], v[32:47]
	v_exp_f32_e32 v90, v90
	v_exp_f32_e32 v91, v91
	v_exp_f32_e32 v92, v92
	v_exp_f32_e32 v93, v93
	v_add_f32_e32 v226, v224, v64
	v_add_f32_e32 v227, v225, v65
	v_exp_f32_e32 v230, v66
	v_exp_f32_e32 v231, v67
	s_waitcnt lgkmcnt(9)
	v_mfma_f32_32x32x16_bf16 v[16:31], v[156:159], v[80:83], v[16:31]
	v_exp_f32_e32 v80, v94
	v_exp_f32_e32 v81, v95
	v_cvt_pk_bf16_f32 v64, v88, v89
	v_cvt_pk_bf16_f32 v65, v90, v91
	v_cvt_pk_bf16_f32 v66, v92, v93
	v_cvt_pk_bf16_f32 v67, v80, v81
	v_exp_f32_e32 v68, v68
	v_exp_f32_e32 v69, v69
	v_mfma_f32_32x32x16_bf16 v[32:47], v[152:155], v[64:67], v[32:47]
	v_exp_f32_e32 v70, v70
	v_exp_f32_e32 v71, v71
	v_add_f32_e32 v82, v228, v226
	v_add_f32_e32 v83, v229, v227
	v_exp_f32_e32 v72, v72
	v_add_f32_e32 v82, v230, v82
	v_add_f32_e32 v83, v231, v83
	v_exp_f32_e32 v73, v73
	v_add_f32_e32 v82, v84, v82
	v_add_f32_e32 v83, v85, v83
	s_waitcnt lgkmcnt(8)
	v_mfma_f32_32x32x16_bf16 v[16:31], v[148:151], v[64:67], v[16:31]
	v_cvt_pk_bf16_f32 v64, v224, v225
	v_cvt_pk_bf16_f32 v65, v230, v231
	v_cvt_pk_bf16_f32 v66, v68, v69
	v_cvt_pk_bf16_f32 v67, v70, v71
	v_add_f32_e64 v82, v68, v82
	v_add_f32_e64 v83, v69, v83
	v_add_f32_e32 v82, v86, v82
	v_add_f32_e32 v83, v87, v83
	s_waitcnt lgkmcnt(7)
	v_mfma_f32_32x32x16_bf16 v[32:47], v[144:147], v[64:67], v[32:47]
	v_add_f32_e64 v68, v70, v82
	v_add_f32_e64 v69, v71, v83
	v_exp_f32_e32 v70, v74
	v_exp_f32_e32 v71, v75
	v_exp_f32_e32 v74, v76
	v_exp_f32_e32 v75, v77
	v_exp_f32_e32 v76, v78
	v_exp_f32_e32 v77, v79
	s_waitcnt lgkmcnt(6)
	v_mfma_f32_32x32x16_bf16 v[16:31], v[140:143], v[64:67], v[16:31]
	v_add_f32_e64 v68, v88, v68
	v_add_f32_e64 v69, v89, v69
	v_cvt_pk_bf16_f32 v64, v72, v73
	v_add_f32_e64 v68, v72, v68
	v_add_f32_e64 v69, v73, v69
	v_cvt_pk_bf16_f32 v65, v70, v71
	v_cvt_pk_bf16_f32 v66, v74, v75
	v_cvt_pk_bf16_f32 v67, v76, v77
	v_add_f32_e32 v68, v90, v68
	v_add_f32_e32 v69, v91, v69
	s_waitcnt lgkmcnt(5)
	v_mfma_f32_32x32x16_bf16 v[32:47], v[136:139], v[64:67], v[32:47]
	v_add_f32_e64 v68, v70, v68
	v_add_f32_e64 v69, v71, v69
	v_add_f32_e64 v68, v92, v68
	v_add_f32_e64 v69, v93, v69
	v_add_f32_e64 v68, v74, v68
	v_add_f32_e64 v69, v75, v69
	v_add_f32_e32 v68, v80, v68
	v_add_f32_e32 v69, v81, v69
	s_waitcnt lgkmcnt(4)
	v_mfma_f32_32x32x16_bf16 v[16:31], v[10:13], v[64:67], v[16:31]
	v_add_f32_e64 v68, v76, v68
	v_add_f32_e64 v69, v77, v69
	v_add_f32_e32 v68, v68, v69
	v_add_f32_e32 v218, v218, v68
	s_branch .Latt_t1

; #define LAS __attribute__((address_space(3)))
; __device__ __forceinline__ void qk_tile(f32x16& s0, f32x16& s1, LAS unsigned char* kb, const bf16x8 (&qr)[6], const f32x16& negm, int r32, int hi) {
;     bf16x8 kf[12];
; #pragma unroll
;     for (int ks = 0; ks < 6; ++ks) { kf[2 * ks] = *(const LAS bf16x8*)(kb + r32 * KPT + ks * 32 + hi * 16); kf[2 * ks + 1] = *(const LAS bf16x8*)(kb + (32 + r32) * KPT + ks * 32 + hi * 16); }
;     __builtin_amdgcn_sched_barrier(0);
; #pragma unroll
;     for (int ks = 0; ks < 6; ++ks) {
;         s0 = __builtin_amdgcn_mfma_f32_32x32x16_bf16(kf[2 * ks], qr[ks], ks == 0 ? negm : s0, 0, 0, 0);
;         s1 = __builtin_amdgcn_mfma_f32_32x32x16_bf16(kf[2 * ks + 1], qr[ks], ks == 0 ? negm : s1, 0, 0, 0);
;     }
; }
.Latt_t1:
	s_waitcnt lgkmcnt(0)
	s_barrier
	s_andn2_b64 vcc, exec, s[44:45]
	s_cbranch_vccnz .LBB0_417
	s_cmp_gt_u32 s84, s57
	s_cselect_b32 s4, s79, 0
	s_lshl_b32 s4, s4, 6
	s_sub_i32 s5, 0xc0, s4
	v_add_u32_e32 v120, s5, v221
	v_add_u32_e32 v184, s5, v222
	s_add_i32 s4, s83, 64
	v_cmp_le_u32_e32 vcc, s4, v220
	s_and_saveexec_b64 s[44:45], vcc
	s_cbranch_execz .Latt_sk2
	ds_read_b128 v[10:13], v241
	ds_read_b128 v[136:139], v241 offset:32
	ds_read_b128 v[140:143], v241 offset:6656
	ds_read_b128 v[144:147], v241 offset:6688
	ds_read_b128 v[148:151], v241 offset:64
	ds_read_b128 v[152:155], v241 offset:96
	ds_read_b128 v[156:159], v241 offset:6720
	ds_read_b128 v[160:163], v241 offset:6752
	ds_read_b128 v[222:225], v241 offset:128
	ds_read_b128 v[226:229], v241 offset:160
	ds_read_b128 v[230:233], v241 offset:6784
	ds_read_b128 v[234:237], v241 offset:6816
	s_waitcnt lgkmcnt(11)
	v_mfma_f32_32x32x16_bf16 v[80:95], v[10:13], v[96:99], v[48:63]
	s_add_i32 s4, s83, 0x7f
	v_cmp_gt_i32_e32 vcc, s4, v175
	s_waitcnt lgkmcnt(9)
	v_mfma_f32_32x32x16_bf16 v[64:79], v[140:143], v[96:99], v[48:63]
	v_mfma_f32_32x32x16_bf16 v[80:95], v[136:139], v[100:103], v[80:95]
	s_waitcnt lgkmcnt(8)
	v_mfma_f32_32x32x16_bf16 v[64:79], v[144:147], v[100:103], v[64:79]
	s_waitcnt lgkmcnt(7)
	v_mfma_f32_32x32x16_bf16 v[80:95], v[148:151], v[104:107], v[80:95]
	s_waitcnt lgkmcnt(5)
	v_mfma_f32_32x32x16_bf16 v[64:79], v[156:159], v[104:107], v[64:79]
	v_mfma_f32_32x32x16_bf16 v[80:95], v[152:155], v[108:111], v[80:95]
	ds_read2_b64 v[152:155], v252 offset0:4 offset1:6
	s_waitcnt lgkmcnt(5)
	v_mfma_f32_32x32x16_bf16 v[64:79], v[160:163], v[108:111], v[64:79]
	ds_read2_b64 v[160:163], v252 offset1:2
	ds_read2_b64 v[156:159], v253 offset0:32 offset1:34
	ds_read2_b64 v[148:151], v253 offset0:36 offset1:38
	ds_read2_b64 v[144:147], v252 offset0:8 offset1:10
	ds_read2_b64 v[140:143], v253 offset0:40 offset1:42
	ds_read2_b64 v[136:139], v252 offset0:12 offset1:14
	ds_read2_b64 v[10:13], v253 offset0:44 offset1:46
	s_waitcnt lgkmcnt(11)
	v_mfma_f32_32x32x16_bf16 v[80:95], v[222:225], v[112:115], v[80:95]
	s_waitcnt lgkmcnt(9)
	v_mfma_f32_32x32x16_bf16 v[64:79], v[230:233], v[112:115], v[64:79]
	v_mfma_f32_32x32x16_bf16 v[80:95], v[226:229], v[116:119], v[80:95]
	s_waitcnt lgkmcnt(8)
	v_mfma_f32_32x32x16_bf16 v[64:79], v[234:237], v[116:119], v[64:79]
	s_waitcnt vmcnt(0)
	ds_write_b128 v210, v[2:5] offset:13312
	s_and_saveexec_b64 s[6:7], s[2:3]
	ds_write_b128 v210, v[6:9] offset:13440
	s_or_b64 exec, exec, s[6:7]
	v_perm_b32 v122, v192, v14, s94
	v_perm_b32 v123, v192, v14, s95
	ds_write2_b32 v254, v122, v123 offset0:128 offset1:162
	v_perm_b32 v122, v193, v15, s94
	v_perm_b32 v123, v193, v15, s95
	ds_write2_b32 v254, v122, v123 offset0:196 offset1:230
	v_min_u32_e32 v120, 0x80ff, v120
	v_add_u32_e32 v186, 1, v184
	v_min_u32_e32 v184, 0x80ff, v184
	v_min_u32_e32 v186, 0x80ff, v186
	v_lshl_add_u32 v122, v120, 12, v238
	v_lshl_add_u32 v124, v120, 6, v239
	v_lshl_add_u32 v184, v184, 12, v174
	v_lshl_add_u32 v186, v186, 12, v174
	global_load_dwordx4 v[120:123], v122, s[98:99]
	s_nop 0
	global_load_dwordx4 v[124:127], v124, s[100:101]
	global_load_dwordx2 v[184:185], v184, s[98:99] offset:128
	global_load_dwordx2 v[186:187], v186, s[98:99] offset:128
	s_and_saveexec_b64 s[46:47], vcc
	s_cbranch_execz .LBB0_434
; __device__ __forceinline__ void sm_pv(f32x16& s0, f32x16& s1, f32x16& o0, f32x16& o1, float& m_run, float& l_run, f32x16& negm, LAS unsigned char* vb, bool domask, int kbase, int qm, int r32, int hi) {
;     ...
;     if (domask) {
;         const int kb0 = kbase + 4 * hi;
; #pragma unroll
;         for (int r = 0; r < 16; ++r) { const int kv = kb0 + (r & 3) + 8 * (r >> 2); if (kv > qm) s0[r] = -INFINITY; if (kv + 32 > qm) s1[r] = -INFINITY; }
;     }
	v_add_u32_e32 v221, s83, v201
	v_add_u32_e32 v223, 0x60, v221
	v_add_u32_e32 v222, 64, v221
	v_cmp_le_u32_e64 s[4:5], v223, v219
	v_cmp_le_u32_e32 vcc, v222, v219
	s_nop 4
	v_cndmask_b32_e64 v64, v244, v64, s[4:5]
	v_cmp_lt_u32_e64 s[4:5], v222, v219
	v_add_u32_e32 v222, 0x61, v221
	v_cmp_le_u32_e64 s[6:7], v222, v219
	v_add_u32_e32 v222, 0x42, v221
	s_nop 0
	v_cndmask_b32_e64 v65, v244, v65, s[6:7]
	v_cmp_le_u32_e64 s[6:7], v222, v219
	v_add_u32_e32 v222, 0x62, v221
	v_cmp_le_u32_e64 s[8:9], v222, v219
	v_add_u32_e32 v222, 0x43, v221
	s_nop 0
	v_cndmask_b32_e64 v66, v244, v66, s[8:9]
	v_cmp_le_u32_e64 s[8:9], v222, v219
	v_add_u32_e32 v222, 0x63, v221
	v_cmp_le_u32_e64 s[10:11], v222, v219
	v_add_u32_e32 v222, 0x48, v221
	s_nop 0
	v_cndmask_b32_e64 v67, v244, v67, s[10:11]
	v_cmp_le_u32_e64 s[10:11], v222, v219
	v_add_u32_e32 v222, 0x68, v221
	v_cmp_le_u32_e64 s[12:13], v222, v219
	v_add_u32_e32 v222, 0x49, v221
	s_nop 0
	v_cndmask_b32_e64 v68, v244, v68, s[12:13]
	v_cmp_le_u32_e64 s[12:13], v222, v219
	v_add_u32_e32 v222, 0x69, v221
	v_cmp_le_u32_e64 s[14:15], v222, v219
	v_add_u32_e32 v222, 0x4a, v221
	s_nop 0
	v_cndmask_b32_e64 v69, v244, v69, s[14:15]
	v_cmp_le_u32_e64 s[14:15], v222, v219
	v_add_u32_e32 v222, 0x6a, v221
	v_cmp_le_u32_e64 s[16:17], v222, v219
	v_add_u32_e32 v222, 0x4b, v221
	s_nop 0
	v_cndmask_b32_e64 v70, v244, v70, s[16:17]
	v_cmp_le_u32_e64 s[16:17], v222, v219
	v_add_u32_e32 v222, 0x6b, v221
	v_cmp_le_u32_e64 s[18:19], v222, v219
	v_add_u32_e32 v222, 0x50, v221
	s_nop 0
	v_cndmask_b32_e64 v71, v244, v71, s[18:19]
	v_cmp_le_u32_e64 s[18:19], v222, v219
	v_add_u32_e32 v222, 0x70, v221
	v_cmp_le_u32_e64 s[20:21], v222, v219
	v_add_u32_e32 v222, 0x51, v221
	s_nop 0
	v_cndmask_b32_e64 v72, v244, v72, s[20:21]
	v_cmp_le_u32_e64 s[20:21], v222, v219
	v_add_u32_e32 v222, 0x71, v221
	v_cmp_le_u32_e64 s[22:23], v222, v219
	v_add_u32_e32 v222, 0x52, v221
	s_nop 0
	v_cndmask_b32_e64 v73, v244, v73, s[22:23]
	v_cmp_le_u32_e64 s[22:23], v222, v219
	v_add_u32_e32 v222, 0x72, v221
	v_cmp_le_u32_e64 s[24:25], v222, v219
	v_add_u32_e32 v222, 0x53, v221
	s_nop 0
	v_cndmask_b32_e64 v74, v244, v74, s[24:25]
	v_cmp_le_u32_e64 s[24:25], v222, v219
	v_add_u32_e32 v222, 0x73, v221
	v_cmp_le_u32_e64 s[26:27], v222, v219
	v_add_u32_e32 v222, 0x58, v221
	s_nop 0
	v_cndmask_b32_e64 v75, v244, v75, s[26:27]
	v_cmp_le_u32_e64 s[26:27], v222, v219
	v_add_u32_e32 v222, 0x78, v221
	v_cmp_le_u32_e64 s[28:29], v222, v219
	v_add_u32_e32 v222, 0x59, v221
	s_nop 0
	v_cndmask_b32_e64 v76, v244, v76, s[28:29]
	v_cmp_le_u32_e64 s[28:29], v222, v219
	v_add_u32_e32 v222, 0x79, v221
	v_cmp_le_u32_e64 s[30:31], v222, v219
	v_add_u32_e32 v222, 0x5a, v221
	s_nop 0
	v_cndmask_b32_e64 v77, v244, v77, s[30:31]
	v_cmp_le_u32_e64 s[30:31], v222, v219
	v_add_u32_e32 v222, 0x7a, v221
	v_cmp_le_u32_e64 s[34:35], v222, v219
	v_add_u32_e32 v222, 0x5b, v221
	v_add_u32_e32 v221, 0x7b, v221
	v_cndmask_b32_e64 v78, v244, v78, s[34:35]
	v_cmp_le_u32_e64 s[34:35], v222, v219
	v_cmp_gt_u32_e64 s[36:37], v221, v219
	s_and_saveexec_b64 s[40:41], s[36:37]
	v_mov_b32_e32 v79, s52
	s_or_b64 exec, exec, s[40:41]
	v_cndmask_b32_e64 v81, v244, v81, s[4:5]
	v_cndmask_b32_e32 v80, v244, v80, vcc
	v_cndmask_b32_e64 v82, v244, v82, s[6:7]
	v_cndmask_b32_e64 v83, v244, v83, s[8:9]
	v_cndmask_b32_e64 v84, v244, v84, s[10:11]
	v_cndmask_b32_e64 v85, v244, v85, s[12:13]
	v_cndmask_b32_e64 v86, v244, v86, s[14:15]
	v_cndmask_b32_e64 v87, v244, v87, s[16:17]
	v_cndmask_b32_e64 v88, v244, v88, s[18:19]
	v_cndmask_b32_e64 v89, v244, v89, s[20:21]
	v_cndmask_b32_e64 v90, v244, v90, s[22:23]
	v_cndmask_b32_e64 v91, v244, v91, s[24:25]
	v_cndmask_b32_e64 v92, v244, v92, s[26:27]
	v_cndmask_b32_e64 v93, v244, v93, s[28:29]
	v_cndmask_b32_e64 v94, v244, v94, s[30:31]
	v_cndmask_b32_e64 v95, v244, v95, s[34:35]

; __device__ __forceinline__ unsigned cvtpk(float lo, float hi) { const f32x2 v = {lo, hi}; const bf16x2_t b = __builtin_convertvector(v, bf16x2_t); return __builtin_bit_cast(unsigned, b); }
; __device__ __forceinline__ void sm_pv(f32x16& s0, f32x16& s1, f32x16& o0, f32x16& o1, float& m_run, float& l_run, f32x16& negm, LAS unsigned char* vb, bool domask, int kbase, int qm, int r32, int hi) {
;     ...
;     f32x2 ps2 = (f32x2){0.f, 0.f};
; #pragma unroll
;     for (int r = 0; r < 16; r += 2) { s0[r] = __builtin_amdgcn_exp2f(s0[r]); s0[r + 1] = __builtin_amdgcn_exp2f(s0[r + 1]); s1[r] = __builtin_amdgcn_exp2f(s1[r]); s1[r + 1] = __builtin_amdgcn_exp2f(s1[r + 1]);
;         ps2 += (f32x2){s0[r], s0[r + 1]}; ps2 += (f32x2){s1[r], s1[r + 1]}; }
;     l_run += ps2[0] + ps2[1];
;     u32x4 pw[4];
; #pragma unroll
;     for (int i = 0; i < 4; ++i) { pw[0][i] = cvtpk(s0[2 * i], s0[2 * i + 1]); pw[1][i] = cvtpk(s0[8 + 2 * i], s0[8 + 2 * i + 1]); pw[2][i] = cvtpk(s1[2 * i], s1[2 * i + 1]); pw[3][i] = cvtpk(s1[8 + 2 * i], s1[8 + 2 * i + 1]); }
; #pragma unroll
;     for (int kk = 0; kk < 4; ++kk) {
;         const bf16x8 pf = __builtin_bit_cast(bf16x8, pw[kk]);
;         { const s16x4 lo = vlo[2 * kk], hh = vhh[2 * kk];
;           const bf16x8 vf = (bf16x8){lo[0], lo[1], lo[2], lo[3], hh[0], hh[1], hh[2], hh[3]};
;           o0 = __builtin_amdgcn_mfma_f32_32x32x16_bf16(vf, pf, o0, 0, 0, 0); }
;         { const s16x4 lo = vlo[2 * kk + 1], hh = vhh[2 * kk + 1];
;           const bf16x8 vf = (bf16x8){lo[0], lo[1], lo[2], lo[3], hh[0], hh[1], hh[2], hh[3]};
;           o1 = __builtin_amdgcn_mfma_f32_32x32x16_bf16(vf, pf, o1, 0, 0, 0); }
;     }
.LBB0_436:
	v_exp_f32_e32 v80, v80
	v_exp_f32_e32 v81, v81
	v_exp_f32_e32 v226, v82
	v_exp_f32_e32 v227, v83
	v_exp_f32_e32 v84, v84
	v_exp_f32_e32 v85, v85
	v_exp_f32_e32 v86, v86
	v_exp_f32_e32 v87, v87
	v_exp_f32_e32 v222, v64
	v_exp_f32_e32 v223, v65
	v_add_f32_e32 v64, 0, v80
	v_add_f32_e32 v65, 0, v81
	v_cvt_pk_bf16_f32 v80, v80, v81
	v_cvt_pk_bf16_f32 v81, v226, v227
	v_cvt_pk_bf16_f32 v82, v84, v85
	v_cvt_pk_bf16_f32 v83, v86, v87
	v_exp_f32_e32 v88, v88
	v_exp_f32_e32 v89, v89
	s_waitcnt lgkmcnt(10)
	v_mfma_f32_32x32x16_bf16 v[32:47], v[160:163], v[80:83], v[32:47]
	v_exp_f32_e32 v90, v90
	v_exp_f32_e32 v91, v91
	v_exp_f32_e32 v92, v92
	v_exp_f32_e32 v93, v93
	v_add_f32_e32 v224, v222, v64
	v_add_f32_e32 v225, v223, v65
	v_exp_f32_e32 v228, v66
	v_exp_f32_e32 v229, v67
	s_waitcnt lgkmcnt(9)
	v_mfma_f32_32x32x16_bf16 v[16:31], v[156:159], v[80:83], v[16:31]
	v_exp_f32_e32 v80, v94
	v_exp_f32_e32 v81, v95
	v_cvt_pk_bf16_f32 v64, v88, v89
	v_cvt_pk_bf16_f32 v65, v90, v91
	v_cvt_pk_bf16_f32 v66, v92, v93
	v_cvt_pk_bf16_f32 v67, v80, v81
	v_exp_f32_e32 v68, v68
	v_exp_f32_e32 v69, v69
	v_mfma_f32_32x32x16_bf16 v[32:47], v[152:155], v[64:67], v[32:47]
	v_exp_f32_e32 v70, v70
	v_exp_f32_e32 v71, v71
	v_add_f32_e32 v82, v226, v224
	v_add_f32_e32 v83, v227, v225
	v_exp_f32_e32 v72, v72
	v_add_f32_e32 v82, v228, v82
	v_add_f32_e32 v83, v229, v83
	v_exp_f32_e32 v73, v73
	v_add_f32_e32 v82, v84, v82
	v_add_f32_e32 v83, v85, v83
	s_waitcnt lgkmcnt(8)
	v_mfma_f32_32x32x16_bf16 v[16:31], v[148:151], v[64:67], v[16:31]
	v_cvt_pk_bf16_f32 v64, v222, v223
	v_cvt_pk_bf16_f32 v65, v228, v229
	v_cvt_pk_bf16_f32 v66, v68, v69
	v_cvt_pk_bf16_f32 v67, v70, v71
	v_add_f32_e64 v82, v68, v82
	v_add_f32_e64 v83, v69, v83
	v_add_f32_e32 v82, v86, v82
	v_add_f32_e32 v83, v87, v83
	s_waitcnt lgkmcnt(7)
	v_mfma_f32_32x32x16_bf16 v[32:47], v[144:147], v[64:67], v[32:47]
	v_add_f32_e64 v68, v70, v82
	v_add_f32_e64 v69, v71, v83
	v_exp_f32_e32 v70, v74
	v_exp_f32_e32 v71, v75
	v_exp_f32_e32 v74, v76
	v_exp_f32_e32 v75, v77
	v_exp_f32_e32 v76, v78
	v_exp_f32_e32 v77, v79
	s_waitcnt lgkmcnt(6)
	v_mfma_f32_32x32x16_bf16 v[16:31], v[140:143], v[64:67], v[16:31]
	v_add_f32_e64 v68, v88, v68
	v_add_f32_e64 v69, v89, v69
	v_cvt_pk_bf16_f32 v64, v72, v73
	v_add_f32_e64 v68, v72, v68
	v_add_f32_e64 v69, v73, v69
	v_cvt_pk_bf16_f32 v65, v70, v71
	v_cvt_pk_bf16_f32 v66, v74, v75
	v_cvt_pk_bf16_f32 v67, v76, v77
	v_add_f32_e32 v68, v90, v68
	v_add_f32_e32 v69, v91, v69
	s_waitcnt lgkmcnt(5)
	v_mfma_f32_32x32x16_bf16 v[32:47], v[136:139], v[64:67], v[32:47]
	v_add_f32_e64 v68, v70, v68
	v_add_f32_e64 v69, v71, v69
	v_add_f32_e64 v68, v92, v68
	v_add_f32_e64 v69, v93, v69
	v_add_f32_e64 v68, v74, v68
	v_add_f32_e64 v69, v75, v69
	v_add_f32_e32 v68, v80, v68
	v_add_f32_e32 v69, v81, v69
	s_waitcnt lgkmcnt(4)
	v_mfma_f32_32x32x16_bf16 v[16:31], v[10:13], v[64:67], v[16:31]
	v_add_f32_e64 v68, v76, v68
	v_add_f32_e64 v69, v77, v69
	v_add_f32_e32 v68, v68, v69
	v_add_f32_e32 v218, v218, v68
	s_branch .Latt_t2

; #define LAS __attribute__((address_space(3)))
; __device__ __forceinline__ void qk_tile(f32x16& s0, f32x16& s1, LAS unsigned char* kb, const bf16x8 (&qr)[6], const f32x16& negm, int r32, int hi) {
;     bf16x8 kf[12];
; #pragma unroll
;     for (int ks = 0; ks < 6; ++ks) { kf[2 * ks] = *(const LAS bf16x8*)(kb + r32 * KPT + ks * 32 + hi * 16); kf[2 * ks + 1] = *(const LAS bf16x8*)(kb + (32 + r32) * KPT + ks * 32 + hi * 16); }
;     __builtin_amdgcn_sched_barrier(0);
; #pragma unroll
;     for (int ks = 0; ks < 6; ++ks) {
;         s0 = __builtin_amdgcn_mfma_f32_32x32x16_bf16(kf[2 * ks], qr[ks], ks == 0 ? negm : s0, 0, 0, 0);
;         s1 = __builtin_amdgcn_mfma_f32_32x32x16_bf16(kf[2 * ks + 1], qr[ks], ks == 0 ? negm : s1, 0, 0, 0);
;     }
.LBB0_443:
	s_add_i32 s85, s84, -3
	s_cmp_lt_u32 s85, s57
	s_cselect_b64 s[44:45], -1, 0
	s_and_b64 s[4:5], s[44:45], exec
	s_cselect_b32 s4, 0, s79
	s_lshl_b32 s4, s4, 6
	s_sub_i32 s5, 0x80, s4
	v_add_u32_e32 v14, s83, v213
	v_add_u32_e32 v15, s83, v173
	v_cmp_le_u32_e32 vcc, s83, v220
	s_and_saveexec_b64 s[46:47], vcc
	s_cbranch_execz .Latt_sk3
	ds_read_b128 v[2:5], v241
	ds_read_b128 v[6:9], v241 offset:32
	ds_read_b128 v[10:13], v241 offset:6656
	ds_read_b128 v[136:139], v241 offset:6688
	ds_read_b128 v[140:143], v241 offset:64
	ds_read_b128 v[144:147], v241 offset:96
	ds_read_b128 v[148:151], v241 offset:6720
	ds_read_b128 v[152:155], v241 offset:6752
	ds_read_b128 v[156:159], v241 offset:128
	ds_read_b128 v[160:163], v241 offset:160
	ds_read_b128 v[222:225], v241 offset:6784
	ds_read_b128 v[226:229], v241 offset:6816
	s_waitcnt lgkmcnt(11)
	v_mfma_f32_32x32x16_bf16 v[80:95], v[2:5], v[96:99], v[48:63]
	s_add_i32 s4, s83, 63
	v_cmp_gt_i32_e32 vcc, s4, v175
	s_waitcnt lgkmcnt(9)
	v_mfma_f32_32x32x16_bf16 v[64:79], v[10:13], v[96:99], v[48:63]
	v_mfma_f32_32x32x16_bf16 v[80:95], v[6:9], v[100:103], v[80:95]
	s_waitcnt lgkmcnt(8)
	v_mfma_f32_32x32x16_bf16 v[64:79], v[136:139], v[100:103], v[64:79]
	s_waitcnt lgkmcnt(7)
	v_mfma_f32_32x32x16_bf16 v[80:95], v[140:143], v[104:107], v[80:95]
	s_waitcnt lgkmcnt(5)
	v_mfma_f32_32x32x16_bf16 v[64:79], v[148:151], v[104:107], v[64:79]
	v_mfma_f32_32x32x16_bf16 v[80:95], v[144:147], v[108:111], v[80:95]
	ds_read2_b64 v[144:147], v252 offset0:4 offset1:6
	s_waitcnt lgkmcnt(5)
	v_mfma_f32_32x32x16_bf16 v[64:79], v[152:155], v[108:111], v[64:79]
	ds_read2_b64 v[152:155], v252 offset1:2
	ds_read2_b64 v[148:151], v253 offset0:32 offset1:34
	ds_read2_b64 v[140:143], v253 offset0:36 offset1:38
	ds_read2_b64 v[136:139], v252 offset0:8 offset1:10
	ds_read2_b64 v[10:13], v253 offset0:40 offset1:42
	ds_read2_b64 v[6:9], v252 offset0:12 offset1:14
	ds_read2_b64 v[2:5], v253 offset0:44 offset1:46
	s_waitcnt lgkmcnt(11)
	v_mfma_f32_32x32x16_bf16 v[80:95], v[156:159], v[112:115], v[80:95]
	s_waitcnt lgkmcnt(9)
	v_mfma_f32_32x32x16_bf16 v[64:79], v[222:225], v[112:115], v[64:79]
	v_mfma_f32_32x32x16_bf16 v[80:95], v[160:163], v[116:119], v[80:95]
	s_waitcnt lgkmcnt(8)
	v_mfma_f32_32x32x16_bf16 v[64:79], v[226:229], v[116:119], v[64:79]
	s_waitcnt vmcnt(0)
	ds_write_b128 v210, v[128:131] offset:13312
	s_and_saveexec_b64 s[6:7], s[2:3]
	ds_write_b128 v210, v[132:135] offset:13440
	s_or_b64 exec, exec, s[6:7]
	v_perm_b32 v120, v190, v188, s94
	v_perm_b32 v121, v190, v188, s95
	ds_write2_b32 v254, v120, v121 offset0:128 offset1:162
	v_perm_b32 v120, v191, v189, s94
	v_perm_b32 v121, v191, v189, s95
	ds_write2_b32 v254, v120, v121 offset0:196 offset1:230
	v_add_u32_e32 v120, s5, v14
	v_add_u32_e32 v184, s5, v15
	v_min_u32_e32 v120, 0x80ff, v120
	v_add_u32_e32 v186, 1, v184
	v_min_u32_e32 v184, 0x80ff, v184
	v_min_u32_e32 v186, 0x80ff, v186
	v_lshl_add_u32 v122, v120, 12, v238
	v_lshl_add_u32 v124, v120, 6, v239
	v_lshl_add_u32 v184, v184, 12, v174
	v_lshl_add_u32 v186, v186, 12, v174
	global_load_dwordx4 v[120:123], v122, s[98:99]
	s_nop 0
	global_load_dwordx4 v[124:127], v124, s[100:101]
	global_load_dwordx2 v[184:185], v184, s[98:99] offset:128
	global_load_dwordx2 v[186:187], v186, s[98:99] offset:128
	s_and_saveexec_b64 s[58:59], vcc
	s_cbranch_execz .LBB0_448
	v_add_u32_e32 v156, s83, v201
	v_add_u32_e32 v157, 32, v156
	v_cmp_ge_i32_e64 s[4:5], v177, v157
	v_add_u32_e32 v157, 33, v156
	v_cmp_ge_i32_e64 s[6:7], v177, v157
	v_add_u32_e32 v157, 2, v156
	v_cmp_le_u32_e32 vcc, v156, v219
	s_nop 2
	v_cndmask_b32_e64 v65, v244, v65, s[6:7]
	v_cmp_ge_i32_e64 s[6:7], v177, v157
	v_add_u32_e32 v157, 34, v156
	v_cmp_ge_i32_e64 s[8:9], v177, v157
	v_add_u32_e32 v157, 3, v156
	v_cndmask_b32_e64 v64, v244, v64, s[4:5]
	v_cndmask_b32_e64 v66, v244, v66, s[8:9]
	v_cmp_ge_i32_e64 s[8:9], v177, v157
	v_add_u32_e32 v157, 35, v156
	v_cmp_ge_i32_e64 s[10:11], v177, v157
	v_add_u32_e32 v157, 8, v156
	v_cmp_gt_i32_e64 s[4:5], v177, v156
	v_cndmask_b32_e64 v67, v244, v67, s[10:11]
	v_cmp_ge_i32_e64 s[10:11], v177, v157
	v_add_u32_e32 v157, 40, v156
	v_cmp_ge_i32_e64 s[12:13], v177, v157
	v_add_u32_e32 v157, 9, v156
	s_nop 0
	v_cndmask_b32_e64 v68, v244, v68, s[12:13]
	v_cmp_ge_i32_e64 s[12:13], v177, v157
	v_add_u32_e32 v157, 41, v156
	v_cmp_ge_i32_e64 s[14:15], v177, v157
	v_add_u32_e32 v157, 10, v156
	s_nop 0
	v_cndmask_b32_e64 v69, v244, v69, s[14:15]
	v_cmp_ge_i32_e64 s[14:15], v177, v157
	v_add_u32_e32 v157, 42, v156
	v_cmp_ge_i32_e64 s[16:17], v177, v157
	v_add_u32_e32 v157, 11, v156
	s_nop 0
	v_cndmask_b32_e64 v70, v244, v70, s[16:17]
	v_cmp_ge_i32_e64 s[16:17], v177, v157
	v_add_u32_e32 v157, 43, v156
	v_cmp_ge_i32_e64 s[18:19], v177, v157
	v_add_u32_e32 v157, 16, v156
	s_nop 0
	v_cndmask_b32_e64 v71, v244, v71, s[18:19]
	v_cmp_ge_i32_e64 s[18:19], v177, v157
	v_add_u32_e32 v157, 48, v156
	v_cmp_ge_i32_e64 s[20:21], v177, v157
	v_add_u32_e32 v157, 17, v156
	s_nop 0
	v_cndmask_b32_e64 v72, v244, v72, s[20:21]
	v_cmp_ge_i32_e64 s[20:21], v177, v157
	v_add_u32_e32 v157, 49, v156
	v_cmp_ge_i32_e64 s[22:23], v177, v157
	v_add_u32_e32 v157, 18, v156
	s_nop 0
	v_cndmask_b32_e64 v73, v244, v73, s[22:23]
	v_cmp_ge_i32_e64 s[22:23], v177, v157
	v_add_u32_e32 v157, 50, v156
	v_cmp_ge_i32_e64 s[24:25], v177, v157
	v_add_u32_e32 v157, 19, v156
	s_nop 0
	v_cndmask_b32_e64 v74, v244, v74, s[24:25]
	v_cmp_ge_i32_e64 s[24:25], v177, v157
	v_add_u32_e32 v157, 51, v156
	v_cmp_ge_i32_e64 s[26:27], v177, v157
	v_add_u32_e32 v157, 24, v156
	s_nop 0
	v_cndmask_b32_e64 v75, v244, v75, s[26:27]
	v_cmp_ge_i32_e64 s[26:27], v177, v157
	v_add_u32_e32 v157, 56, v156
	v_cmp_ge_i32_e64 s[28:29], v177, v157
	v_add_u32_e32 v157, 25, v156
	s_nop 0
	v_cndmask_b32_e64 v76, v244, v76, s[28:29]
	v_cmp_ge_i32_e64 s[28:29], v177, v157
	v_add_u32_e32 v157, 57, v156
	v_cmp_ge_i32_e64 s[30:31], v177, v157
	v_add_u32_e32 v157, 26, v156
	s_nop 0
	v_cndmask_b32_e64 v77, v244, v77, s[30:31]
	v_cmp_ge_i32_e64 s[30:31], v177, v157
	v_add_u32_e32 v157, 58, v156
	v_cmp_ge_i32_e64 s[34:35], v177, v157
	v_add_u32_e32 v157, 27, v156
	v_add_u32_e32 v156, 59, v156
	v_cndmask_b32_e64 v78, v244, v78, s[34:35]
	v_cmp_ge_i32_e64 s[34:35], v177, v157
	v_cmp_lt_i32_e64 s[36:37], v177, v156
	s_and_saveexec_b64 s[40:41], s[36:37]
	v_mov_b32_e32 v79, s52
	s_or_b64 exec, exec, s[40:41]
	v_cndmask_b32_e32 v80, v244, v80, vcc
	v_cndmask_b32_e64 v81, v244, v81, s[4:5]
	v_cndmask_b32_e64 v82, v244, v82, s[6:7]
	v_cndmask_b32_e64 v83, v244, v83, s[8:9]
	v_cndmask_b32_e64 v84, v244, v84, s[10:11]
	v_cndmask_b32_e64 v85, v244, v85, s[12:13]
	v_cndmask_b32_e64 v86, v244, v86, s[14:15]
	v_cndmask_b32_e64 v87, v244, v87, s[16:17]
	v_cndmask_b32_e64 v88, v244, v88, s[18:19]
	v_cndmask_b32_e64 v89, v244, v89, s[20:21]
	v_cndmask_b32_e64 v90, v244, v90, s[22:23]
	v_cndmask_b32_e64 v91, v244, v91, s[24:25]
	v_cndmask_b32_e64 v92, v244, v92, s[26:27]
	v_cndmask_b32_e64 v93, v244, v93, s[28:29]
	v_cndmask_b32_e64 v94, v244, v94, s[30:31]
	v_cndmask_b32_e64 v95, v244, v95, s[34:35]

; __device__ __forceinline__ unsigned cvtpk(float lo, float hi) { const f32x2 v = {lo, hi}; const bf16x2_t b = __builtin_convertvector(v, bf16x2_t); return __builtin_bit_cast(unsigned, b); }
; __device__ __forceinline__ void sm_pv(f32x16& s0, f32x16& s1, f32x16& o0, f32x16& o1, float& m_run, float& l_run, f32x16& negm, LAS unsigned char* vb, bool domask, int kbase, int qm, int r32, int hi) {
;     ...
;     f32x2 ps2 = (f32x2){0.f, 0.f};
; #pragma unroll
;     for (int r = 0; r < 16; r += 2) { s0[r] = __builtin_amdgcn_exp2f(s0[r]); s0[r + 1] = __builtin_amdgcn_exp2f(s0[r + 1]); s1[r] = __builtin_amdgcn_exp2f(s1[r]); s1[r + 1] = __builtin_amdgcn_exp2f(s1[r + 1]);
;         ps2 += (f32x2){s0[r], s0[r + 1]}; ps2 += (f32x2){s1[r], s1[r + 1]}; }
;     l_run += ps2[0] + ps2[1];
;     u32x4 pw[4];
; #pragma unroll
;     for (int i = 0; i < 4; ++i) { pw[0][i] = cvtpk(s0[2 * i], s0[2 * i + 1]); pw[1][i] = cvtpk(s0[8 + 2 * i], s0[8 + 2 * i + 1]); pw[2][i] = cvtpk(s1[2 * i], s1[2 * i + 1]); pw[3][i] = cvtpk(s1[8 + 2 * i], s1[8 + 2 * i + 1]); }
; #pragma unroll
;     for (int kk = 0; kk < 4; ++kk) {
;         const bf16x8 pf = __builtin_bit_cast(bf16x8, pw[kk]);
;         { const s16x4 lo = vlo[2 * kk], hh = vhh[2 * kk];
;           const bf16x8 vf = (bf16x8){lo[0], lo[1], lo[2], lo[3], hh[0], hh[1], hh[2], hh[3]};
;           o0 = __builtin_amdgcn_mfma_f32_32x32x16_bf16(vf, pf, o0, 0, 0, 0); }
;         { const s16x4 lo = vlo[2 * kk + 1], hh = vhh[2 * kk + 1];
;           const bf16x8 vf = (bf16x8){lo[0], lo[1], lo[2], lo[3], hh[0], hh[1], hh[2], hh[3]};
;           o1 = __builtin_amdgcn_mfma_f32_32x32x16_bf16(vf, pf, o1, 0, 0, 0); }
;     }
.LBB0_450:
	v_exp_f32_e32 v80, v80
	v_exp_f32_e32 v81, v81
	v_exp_f32_e32 v160, v82
	v_exp_f32_e32 v161, v83
	v_exp_f32_e32 v84, v84
	v_exp_f32_e32 v85, v85
	v_exp_f32_e32 v86, v86
	v_exp_f32_e32 v87, v87
	v_exp_f32_e32 v156, v64
	v_exp_f32_e32 v157, v65
	v_add_f32_e32 v64, 0, v80
	v_add_f32_e32 v65, 0, v81
	v_cvt_pk_bf16_f32 v80, v80, v81
	v_cvt_pk_bf16_f32 v81, v160, v161
	v_cvt_pk_bf16_f32 v82, v84, v85
	v_cvt_pk_bf16_f32 v83, v86, v87
	v_exp_f32_e32 v88, v88
	v_exp_f32_e32 v89, v89
	s_waitcnt lgkmcnt(10)
	v_mfma_f32_32x32x16_bf16 v[32:47], v[152:155], v[80:83], v[32:47]
	v_exp_f32_e32 v90, v90
	v_exp_f32_e32 v91, v91
	v_exp_f32_e32 v92, v92
	v_exp_f32_e32 v93, v93
	v_add_f32_e32 v158, v156, v64
	v_add_f32_e32 v159, v157, v65
	v_exp_f32_e32 v162, v66
	v_exp_f32_e32 v163, v67
	s_waitcnt lgkmcnt(9)
	v_mfma_f32_32x32x16_bf16 v[16:31], v[148:151], v[80:83], v[16:31]
	v_exp_f32_e32 v80, v94
	v_exp_f32_e32 v81, v95
	v_cvt_pk_bf16_f32 v64, v88, v89
	v_cvt_pk_bf16_f32 v65, v90, v91
	v_cvt_pk_bf16_f32 v66, v92, v93
	v_cvt_pk_bf16_f32 v67, v80, v81
	v_exp_f32_e32 v68, v68
	v_exp_f32_e32 v69, v69
	v_mfma_f32_32x32x16_bf16 v[32:47], v[144:147], v[64:67], v[32:47]
	v_exp_f32_e32 v70, v70
	v_exp_f32_e32 v71, v71
	v_add_f32_e32 v82, v160, v158
	v_add_f32_e32 v83, v161, v159
	v_exp_f32_e32 v72, v72
	v_add_f32_e32 v82, v162, v82
	v_add_f32_e32 v83, v163, v83
	v_exp_f32_e32 v73, v73
	v_add_f32_e32 v82, v84, v82
	v_add_f32_e32 v83, v85, v83
	s_waitcnt lgkmcnt(8)
	v_mfma_f32_32x32x16_bf16 v[16:31], v[140:143], v[64:67], v[16:31]
	v_cvt_pk_bf16_f32 v64, v156, v157
	v_cvt_pk_bf16_f32 v65, v162, v163
	v_cvt_pk_bf16_f32 v66, v68, v69
	v_cvt_pk_bf16_f32 v67, v70, v71
	v_add_f32_e64 v82, v68, v82
	v_add_f32_e64 v83, v69, v83
	v_add_f32_e32 v82, v86, v82
	v_add_f32_e32 v83, v87, v83
	s_waitcnt lgkmcnt(7)
	v_mfma_f32_32x32x16_bf16 v[32:47], v[136:139], v[64:67], v[32:47]
	v_add_f32_e64 v68, v70, v82
	v_add_f32_e64 v69, v71, v83
	v_exp_f32_e32 v70, v74
	v_exp_f32_e32 v71, v75
	v_exp_f32_e32 v74, v76
	v_exp_f32_e32 v75, v77
	v_add_f32_e32 v68, v88, v68
	v_add_f32_e32 v69, v89, v69
	s_waitcnt lgkmcnt(6)
	v_mfma_f32_32x32x16_bf16 v[16:31], v[10:13], v[64:67], v[16:31]
	v_exp_f32_e32 v64, v78
	v_exp_f32_e32 v65, v79
	v_add_f32_e32 v68, v72, v68
	v_add_f32_e32 v69, v73, v69
	v_cvt_pk_bf16_f32 v10, v72, v73
	v_add_f32_e32 v68, v90, v68
	v_add_f32_e32 v69, v91, v69
	v_cvt_pk_bf16_f32 v11, v70, v71
	v_cvt_pk_bf16_f32 v12, v74, v75
	v_cvt_pk_bf16_f32 v13, v64, v65
	s_waitcnt lgkmcnt(5)
	s_nop 0
	v_mfma_f32_32x32x16_bf16 v[32:47], v[6:9], v[10:13], v[32:47]
	v_add_f32_e64 v6, v70, v68
	v_add_f32_e64 v7, v71, v69
	v_add_f32_e64 v6, v92, v6
	v_add_f32_e64 v7, v93, v7
	v_add_f32_e64 v6, v74, v6
	v_add_f32_e64 v7, v75, v7
	v_add_f32_e32 v6, v80, v6
	v_add_f32_e32 v7, v81, v7
	s_waitcnt lgkmcnt(4)
	v_mfma_f32_32x32x16_bf16 v[16:31], v[2:5], v[10:13], v[16:31]
	v_add_f32_e64 v6, v64, v6
	v_add_f32_e64 v7, v65, v7
	v_add_f32_e32 v6, v6, v7
	v_add_f32_e32 v218, v218, v6
	s_branch .Latt_t3

; #define LAS __attribute__((address_space(3)))
; __device__ __forceinline__ void qk_tile(f32x16& s0, f32x16& s1, LAS unsigned char* kb, const bf16x8 (&qr)[6], const f32x16& negm, int r32, int hi) {
;     bf16x8 kf[12];
; #pragma unroll
;     for (int ks = 0; ks < 6; ++ks) { kf[2 * ks] = *(const LAS bf16x8*)(kb + r32 * KPT + ks * 32 + hi * 16); kf[2 * ks + 1] = *(const LAS bf16x8*)(kb + (32 + r32) * KPT + ks * 32 + hi * 16); }
;     __builtin_amdgcn_sched_barrier(0);
; #pragma unroll
;     for (int ks = 0; ks < 6; ++ks) {
;         s0 = __builtin_amdgcn_mfma_f32_32x32x16_bf16(kf[2 * ks], qr[ks], ks == 0 ? negm : s0, 0, 0, 0);
;         s1 = __builtin_amdgcn_mfma_f32_32x32x16_bf16(kf[2 * ks + 1], qr[ks], ks == 0 ? negm : s1, 0, 0, 0);
;     }
.Latt_t3:
	s_waitcnt lgkmcnt(0)
	s_barrier
	s_andn2_b64 vcc, exec, s[44:45]
	s_cbranch_vccnz .LBB0_442
	s_cmp_gt_u32 s84, s57
	s_cselect_b32 s4, s79, 0
	s_lshl_b32 s4, s4, 6
	s_sub_i32 s5, 0xc0, s4
	s_add_i32 s4, s83, 64
	v_cmp_le_u32_e32 vcc, s4, v220
	s_and_saveexec_b64 s[44:45], vcc
	s_cbranch_execz .Latt_sk4
	ds_read_b128 v[2:5], v240 offset:13312
	ds_read_b128 v[6:9], v240 offset:13344
	ds_read_b128 v[10:13], v240 offset:19968
	ds_read_b128 v[136:139], v240 offset:20000
	ds_read_b128 v[140:143], v240 offset:13376
	ds_read_b128 v[144:147], v240 offset:13408
	ds_read_b128 v[148:151], v240 offset:20032
	ds_read_b128 v[152:155], v240 offset:20064
	ds_read_b128 v[156:159], v240 offset:13440
	ds_read_b128 v[160:163], v240 offset:13472
	ds_read_b128 v[222:225], v240 offset:20096
	ds_read_b128 v[226:229], v240 offset:20128
	s_waitcnt lgkmcnt(11)
	v_mfma_f32_32x32x16_bf16 v[80:95], v[2:5], v[96:99], v[48:63]
	s_add_i32 s4, s83, 0x7f
	v_cmp_gt_i32_e32 vcc, s4, v175
	s_waitcnt lgkmcnt(9)
	v_mfma_f32_32x32x16_bf16 v[64:79], v[10:13], v[96:99], v[48:63]
	v_mfma_f32_32x32x16_bf16 v[80:95], v[6:9], v[100:103], v[80:95]
	s_waitcnt lgkmcnt(8)
	v_mfma_f32_32x32x16_bf16 v[64:79], v[136:139], v[100:103], v[64:79]
	s_waitcnt lgkmcnt(7)
	v_mfma_f32_32x32x16_bf16 v[80:95], v[140:143], v[104:107], v[80:95]
	s_waitcnt lgkmcnt(5)
	v_mfma_f32_32x32x16_bf16 v[64:79], v[148:151], v[104:107], v[64:79]
	v_mfma_f32_32x32x16_bf16 v[80:95], v[144:147], v[108:111], v[80:95]
	ds_read2_b64 v[144:147], v250 offset0:68 offset1:70
	s_waitcnt lgkmcnt(5)
	v_mfma_f32_32x32x16_bf16 v[64:79], v[152:155], v[108:111], v[64:79]
	ds_read2_b64 v[152:155], v250 offset0:64 offset1:66
	ds_read2_b64 v[148:151], v251 offset0:96 offset1:98
	ds_read2_b64 v[140:143], v251 offset0:100 offset1:102
	ds_read2_b64 v[136:139], v250 offset0:72 offset1:74
	ds_read2_b64 v[10:13], v251 offset0:104 offset1:106
	ds_read2_b64 v[6:9], v250 offset0:76 offset1:78
	ds_read2_b64 v[2:5], v251 offset0:108 offset1:110
	s_waitcnt lgkmcnt(11)
	v_mfma_f32_32x32x16_bf16 v[80:95], v[156:159], v[112:115], v[80:95]
	s_waitcnt lgkmcnt(9)
	v_mfma_f32_32x32x16_bf16 v[64:79], v[222:225], v[112:115], v[64:79]
	v_mfma_f32_32x32x16_bf16 v[80:95], v[160:163], v[116:119], v[80:95]
	s_waitcnt lgkmcnt(8)
	v_mfma_f32_32x32x16_bf16 v[64:79], v[226:229], v[116:119], v[64:79]
	s_waitcnt vmcnt(0)
	ds_write_b128 v210, v[120:123]
	s_and_saveexec_b64 s[6:7], s[2:3]
	ds_write_b128 v210, v[124:127] offset:128
	s_or_b64 exec, exec, s[6:7]
	v_perm_b32 v128, v186, v184, s94
	v_perm_b32 v129, v186, v184, s95
	ds_write2_b32 v214, v128, v129 offset1:34
	v_perm_b32 v128, v187, v185, s94
	v_perm_b32 v129, v187, v185, s95
	ds_write2_b32 v214, v128, v129 offset0:68 offset1:102
	v_add_u32_e32 v128, s5, v14
	v_add_u32_e32 v188, s5, v15
	v_min_u32_e32 v128, 0x80ff, v128
	v_add_u32_e32 v190, 1, v188
	v_min_u32_e32 v188, 0x80ff, v188
	v_min_u32_e32 v190, 0x80ff, v190
	v_lshl_add_u32 v130, v128, 12, v238
	v_lshl_add_u32 v132, v128, 6, v239
	v_lshl_add_u32 v188, v188, 12, v174
	v_lshl_add_u32 v190, v190, 12, v174
	global_load_dwordx4 v[128:131], v130, s[98:99]
	s_nop 0
	global_load_dwordx4 v[132:135], v132, s[100:101]
	global_load_dwordx2 v[188:189], v188, s[98:99] offset:128
	global_load_dwordx2 v[190:191], v190, s[98:99] offset:128
	s_and_saveexec_b64 s[46:47], vcc
	s_cbranch_execz .LBB0_459
; __device__ __forceinline__ void sm_pv(f32x16& s0, f32x16& s1, f32x16& o0, f32x16& o1, float& m_run, float& l_run, f32x16& negm, LAS unsigned char* vb, bool domask, int kbase, int qm, int r32, int hi) {
;     ...
;     if (domask) {
;         const int kb0 = kbase + 4 * hi;
; #pragma unroll
;         for (int r = 0; r < 16; ++r) { const int kv = kb0 + (r & 3) + 8 * (r >> 2); if (kv > qm) s0[r] = -INFINITY; if (kv + 32 > qm) s1[r] = -INFINITY; }
;     }
	v_add_u32_e32 v14, s83, v201
	v_add_u32_e32 v156, 0x60, v14
	v_add_u32_e32 v15, 64, v14
	v_cmp_le_u32_e64 s[4:5], v156, v219
	v_cmp_le_u32_e32 vcc, v15, v219
	s_nop 4
	v_cndmask_b32_e64 v64, v244, v64, s[4:5]
	v_cmp_lt_u32_e64 s[4:5], v15, v219
	v_add_u32_e32 v15, 0x61, v14
	v_cmp_le_u32_e64 s[6:7], v15, v219
	v_add_u32_e32 v15, 0x42, v14
	s_nop 0
	v_cndmask_b32_e64 v65, v244, v65, s[6:7]
	v_cmp_le_u32_e64 s[6:7], v15, v219
	v_add_u32_e32 v15, 0x62, v14
	v_cmp_le_u32_e64 s[8:9], v15, v219
	v_add_u32_e32 v15, 0x43, v14
	s_nop 0
	v_cndmask_b32_e64 v66, v244, v66, s[8:9]
	v_cmp_le_u32_e64 s[8:9], v15, v219
	v_add_u32_e32 v15, 0x63, v14
	v_cmp_le_u32_e64 s[10:11], v15, v219
	v_add_u32_e32 v15, 0x48, v14
	s_nop 0
	v_cndmask_b32_e64 v67, v244, v67, s[10:11]
	v_cmp_le_u32_e64 s[10:11], v15, v219
	v_add_u32_e32 v15, 0x68, v14
	v_cmp_le_u32_e64 s[12:13], v15, v219
	v_add_u32_e32 v15, 0x49, v14
	s_nop 0
	v_cndmask_b32_e64 v68, v244, v68, s[12:13]
	v_cmp_le_u32_e64 s[12:13], v15, v219
	v_add_u32_e32 v15, 0x69, v14
	v_cmp_le_u32_e64 s[14:15], v15, v219
	v_add_u32_e32 v15, 0x4a, v14
	s_nop 0
	v_cndmask_b32_e64 v69, v244, v69, s[14:15]
	v_cmp_le_u32_e64 s[14:15], v15, v219
	v_add_u32_e32 v15, 0x6a, v14
	v_cmp_le_u32_e64 s[16:17], v15, v219
	v_add_u32_e32 v15, 0x4b, v14
	s_nop 0
	v_cndmask_b32_e64 v70, v244, v70, s[16:17]
	v_cmp_le_u32_e64 s[16:17], v15, v219
	v_add_u32_e32 v15, 0x6b, v14
	v_cmp_le_u32_e64 s[18:19], v15, v219
	v_add_u32_e32 v15, 0x50, v14
	s_nop 0
	v_cndmask_b32_e64 v71, v244, v71, s[18:19]
	v_cmp_le_u32_e64 s[18:19], v15, v219
	v_add_u32_e32 v15, 0x70, v14
	v_cmp_le_u32_e64 s[20:21], v15, v219
	v_add_u32_e32 v15, 0x51, v14
	s_nop 0
	v_cndmask_b32_e64 v72, v244, v72, s[20:21]
	v_cmp_le_u32_e64 s[20:21], v15, v219
	v_add_u32_e32 v15, 0x71, v14
	v_cmp_le_u32_e64 s[22:23], v15, v219
	v_add_u32_e32 v15, 0x52, v14
	s_nop 0
	v_cndmask_b32_e64 v73, v244, v73, s[22:23]
	v_cmp_le_u32_e64 s[22:23], v15, v219
	v_add_u32_e32 v15, 0x72, v14
	v_cmp_le_u32_e64 s[24:25], v15, v219
	v_add_u32_e32 v15, 0x53, v14
	s_nop 0
	v_cndmask_b32_e64 v74, v244, v74, s[24:25]
	v_cmp_le_u32_e64 s[24:25], v15, v219
	v_add_u32_e32 v15, 0x73, v14
	v_cmp_le_u32_e64 s[26:27], v15, v219
	v_add_u32_e32 v15, 0x58, v14
	s_nop 0
	v_cndmask_b32_e64 v75, v244, v75, s[26:27]
	v_cmp_le_u32_e64 s[26:27], v15, v219
	v_add_u32_e32 v15, 0x78, v14
	v_cmp_le_u32_e64 s[28:29], v15, v219
	v_add_u32_e32 v15, 0x59, v14
	s_nop 0
	v_cndmask_b32_e64 v76, v244, v76, s[28:29]
	v_cmp_le_u32_e64 s[28:29], v15, v219
	v_add_u32_e32 v15, 0x79, v14
	v_cmp_le_u32_e64 s[30:31], v15, v219
	v_add_u32_e32 v15, 0x5a, v14
	s_nop 0
	v_cndmask_b32_e64 v77, v244, v77, s[30:31]
	v_cmp_le_u32_e64 s[30:31], v15, v219
	v_add_u32_e32 v15, 0x7a, v14
	v_cmp_le_u32_e64 s[34:35], v15, v219
	v_add_u32_e32 v15, 0x5b, v14
	v_add_u32_e32 v14, 0x7b, v14
	v_cndmask_b32_e64 v78, v244, v78, s[34:35]
	v_cmp_le_u32_e64 s[34:35], v15, v219
	v_cmp_gt_u32_e64 s[36:37], v14, v219
	s_and_saveexec_b64 s[40:41], s[36:37]
	v_mov_b32_e32 v79, s52
	s_or_b64 exec, exec, s[40:41]
	v_cndmask_b32_e64 v81, v244, v81, s[4:5]
	v_cndmask_b32_e32 v80, v244, v80, vcc
	v_cndmask_b32_e64 v82, v244, v82, s[6:7]
	v_cndmask_b32_e64 v83, v244, v83, s[8:9]
	v_cndmask_b32_e64 v84, v244, v84, s[10:11]
	v_cndmask_b32_e64 v85, v244, v85, s[12:13]
	v_cndmask_b32_e64 v86, v244, v86, s[14:15]
	v_cndmask_b32_e64 v87, v244, v87, s[16:17]
	v_cndmask_b32_e64 v88, v244, v88, s[18:19]
	v_cndmask_b32_e64 v89, v244, v89, s[20:21]
	v_cndmask_b32_e64 v90, v244, v90, s[22:23]
	v_cndmask_b32_e64 v91, v244, v91, s[24:25]
	v_cndmask_b32_e64 v92, v244, v92, s[26:27]
	v_cndmask_b32_e64 v93, v244, v93, s[28:29]
	v_cndmask_b32_e64 v94, v244, v94, s[30:31]
	v_cndmask_b32_e64 v95, v244, v95, s[34:35]

; __device__ __forceinline__ unsigned cvtpk(float lo, float hi) { const f32x2 v = {lo, hi}; const bf16x2_t b = __builtin_convertvector(v, bf16x2_t); return __builtin_bit_cast(unsigned, b); }
; __device__ __forceinline__ void sm_pv(f32x16& s0, f32x16& s1, f32x16& o0, f32x16& o1, float& m_run, float& l_run, f32x16& negm, LAS unsigned char* vb, bool domask, int kbase, int qm, int r32, int hi) {
;     ...
;     f32x2 ps2 = (f32x2){0.f, 0.f};
; #pragma unroll
;     for (int r = 0; r < 16; r += 2) { s0[r] = __builtin_amdgcn_exp2f(s0[r]); s0[r + 1] = __builtin_amdgcn_exp2f(s0[r + 1]); s1[r] = __builtin_amdgcn_exp2f(s1[r]); s1[r + 1] = __builtin_amdgcn_exp2f(s1[r + 1]);
;         ps2 += (f32x2){s0[r], s0[r + 1]}; ps2 += (f32x2){s1[r], s1[r + 1]}; }
;     l_run += ps2[0] + ps2[1];
;     u32x4 pw[4];
; #pragma unroll
;     for (int i = 0; i < 4; ++i) { pw[0][i] = cvtpk(s0[2 * i], s0[2 * i + 1]); pw[1][i] = cvtpk(s0[8 + 2 * i], s0[8 + 2 * i + 1]); pw[2][i] = cvtpk(s1[2 * i], s1[2 * i + 1]); pw[3][i] = cvtpk(s1[8 + 2 * i], s1[8 + 2 * i + 1]); }
; #pragma unroll
;     for (int kk = 0; kk < 4; ++kk) {
;         const bf16x8 pf = __builtin_bit_cast(bf16x8, pw[kk]);
;         { const s16x4 lo = vlo[2 * kk], hh = vhh[2 * kk];
;           const bf16x8 vf = (bf16x8){lo[0], lo[1], lo[2], lo[3], hh[0], hh[1], hh[2], hh[3]};
;           o0 = __builtin_amdgcn_mfma_f32_32x32x16_bf16(vf, pf, o0, 0, 0, 0); }
;         { const s16x4 lo = vlo[2 * kk + 1], hh = vhh[2 * kk + 1];
;           const bf16x8 vf = (bf16x8){lo[0], lo[1], lo[2], lo[3], hh[0], hh[1], hh[2], hh[3]};
;           o1 = __builtin_amdgcn_mfma_f32_32x32x16_bf16(vf, pf, o1, 0, 0, 0); }
;     }
.LBB0_461:
	v_exp_f32_e32 v14, v80
	v_exp_f32_e32 v15, v81
	v_exp_f32_e32 v160, v82
	v_exp_f32_e32 v161, v83
	v_exp_f32_e32 v84, v84
	v_exp_f32_e32 v85, v85
	v_exp_f32_e32 v86, v86
	v_exp_f32_e32 v87, v87
	v_cvt_pk_bf16_f32 v80, v14, v15
	v_cvt_pk_bf16_f32 v81, v160, v161
	v_cvt_pk_bf16_f32 v82, v84, v85
	v_cvt_pk_bf16_f32 v83, v86, v87
	v_exp_f32_e32 v156, v64
	v_exp_f32_e32 v157, v65
	s_waitcnt lgkmcnt(10)
	v_mfma_f32_32x32x16_bf16 v[32:47], v[152:155], v[80:83], v[32:47]
	v_exp_f32_e32 v88, v88
	v_exp_f32_e32 v89, v89
	v_exp_f32_e32 v90, v90
	v_exp_f32_e32 v91, v91
	v_exp_f32_e32 v92, v92
	v_exp_f32_e32 v93, v93
	v_add_f32_e32 v64, 0, v14
	v_add_f32_e32 v65, 0, v15
	s_waitcnt lgkmcnt(9)
	v_mfma_f32_32x32x16_bf16 v[16:31], v[148:151], v[80:83], v[16:31]
	v_exp_f32_e32 v80, v94
	v_exp_f32_e32 v81, v95
	v_add_f32_e32 v158, v156, v64
	v_add_f32_e32 v159, v157, v65
	v_exp_f32_e32 v162, v66
	v_exp_f32_e32 v163, v67
	v_cvt_pk_bf16_f32 v64, v88, v89
	v_cvt_pk_bf16_f32 v65, v90, v91
	v_cvt_pk_bf16_f32 v66, v92, v93
	v_cvt_pk_bf16_f32 v67, v80, v81
	v_exp_f32_e32 v14, v68
	v_exp_f32_e32 v15, v69
	v_mfma_f32_32x32x16_bf16 v[32:47], v[144:147], v[64:67], v[32:47]
	v_exp_f32_e32 v70, v70
	v_exp_f32_e32 v71, v71
	v_add_f32_e32 v68, v160, v158
	v_add_f32_e32 v69, v161, v159
	v_exp_f32_e32 v72, v72
	v_add_f32_e32 v68, v162, v68
	v_add_f32_e32 v69, v163, v69
	v_exp_f32_e32 v73, v73
	v_add_f32_e32 v68, v84, v68
	v_add_f32_e32 v69, v85, v69
	s_waitcnt lgkmcnt(8)
	v_mfma_f32_32x32x16_bf16 v[16:31], v[140:143], v[64:67], v[16:31]
	v_cvt_pk_bf16_f32 v64, v156, v157
	v_cvt_pk_bf16_f32 v65, v162, v163
	v_cvt_pk_bf16_f32 v66, v14, v15
	v_cvt_pk_bf16_f32 v67, v70, v71
	v_add_f32_e64 v68, v14, v68
	v_add_f32_e64 v69, v15, v69
	v_add_f32_e32 v68, v86, v68
	v_add_f32_e32 v69, v87, v69
	s_waitcnt lgkmcnt(7)
	v_mfma_f32_32x32x16_bf16 v[32:47], v[136:139], v[64:67], v[32:47]
	v_add_f32_e64 v14, v70, v68
	v_add_f32_e64 v15, v71, v69
	v_exp_f32_e32 v68, v74
	v_exp_f32_e32 v69, v75
	v_exp_f32_e32 v70, v76
	v_exp_f32_e32 v71, v77
	v_add_f32_e32 v14, v88, v14
	v_add_f32_e32 v15, v89, v15
	s_waitcnt lgkmcnt(6)
	v_mfma_f32_32x32x16_bf16 v[16:31], v[10:13], v[64:67], v[16:31]
	v_exp_f32_e32 v64, v78
	v_exp_f32_e32 v65, v79
	v_add_f32_e32 v14, v72, v14
	v_add_f32_e32 v15, v73, v15
	v_cvt_pk_bf16_f32 v10, v72, v73
	v_cvt_pk_bf16_f32 v11, v68, v69
	v_cvt_pk_bf16_f32 v12, v70, v71
	v_cvt_pk_bf16_f32 v13, v64, v65
	v_add_f32_e32 v14, v90, v14
	v_add_f32_e32 v15, v91, v15
	s_waitcnt lgkmcnt(5)
	v_mfma_f32_32x32x16_bf16 v[32:47], v[6:9], v[10:13], v[32:47]
	v_add_f32_e64 v6, v68, v14
	v_add_f32_e64 v7, v69, v15
	v_add_f32_e64 v6, v92, v6
	v_add_f32_e64 v7, v93, v7
	v_add_f32_e64 v6, v70, v6
	v_add_f32_e64 v7, v71, v7
	v_add_f32_e32 v6, v80, v6
	v_add_f32_e32 v7, v81, v7
	s_waitcnt lgkmcnt(4)
	v_mfma_f32_32x32x16_bf16 v[16:31], v[2:5], v[10:13], v[16:31]
	v_add_f32_e64 v6, v64, v6
	v_add_f32_e64 v7, v65, v7
	v_add_f32_e32 v6, v6, v7
	v_add_f32_e32 v218, v218, v6
	s_branch .Latt_t4
